# in-proj epilogue: 16-byte stores via v_permlane16_swap for full N-tiles; ph3 transposes split between both workgroup halves
# speedup vs baseline: 1.0151x; 1.0045x over previous
.LBB0_329:
	s_cmp_lt_i32 s10, 6
	s_cbranch_scc1 .Linp_fast
	v_lshl_add_u32 v156, s10, 8, v142
	v_add_u32_e32 v138, s25, v140
	v_mov_b64_e32 v[136:137], s[30:31]
	v_mad_i64_i32 v[136:137], s[2:3], v138, s73, v[136:137]
	v_cmp_gt_i32_e32 vcc, s77, v156
	s_and_saveexec_b64 s[2:3], vcc
	s_cbranch_execz .LBB0_331
	v_lshl_add_u64 v[152:153], v[156:157], 1, v[136:137]
	v_cvt_pk_bf16_f32 v150, v124, v125
	v_cvt_pk_bf16_f32 v151, v126, v127
	global_store_dwordx2 v[152:153], v[150:151], off

.Linp_fast:
	v_lshl_add_u32 v156, s10, 8, v142
	v_add_u32_e32 v138, s25, v140
	v_and_b32_e32 v162, 16, v197
	v_lshrrev_b32_e32 v162, 4, v162
	v_mul_u32_u24_e32 v162, 40, v162
	v_sub_u32_e32 v162, 32, v162
	v_lshl_add_u32 v164, v156, 1, v162
	v_mov_b32_e32 v165, 0
	v_mov_b64_e32 v[136:137], s[30:31]
	v_mad_i64_i32 v[182:183], s[2:3], v138, s73, v[136:137]
	v_lshl_add_u64 v[182:183], v[182:183], 0, v[164:165]
	v_cvt_pk_bf16_f32 v166, v120, v121
	v_cvt_pk_bf16_f32 v167, v122, v123
	v_cvt_pk_bf16_f32 v168, v124, v125
	v_cvt_pk_bf16_f32 v169, v126, v127
	s_nop 1
	v_permlane16_swap_b32_e32 v166, v168
	v_permlane16_swap_b32_e32 v167, v169
	global_store_dwordx4 v[182:183], v[166:169], off
	v_cvt_pk_bf16_f32 v170, v112, v113
	v_cvt_pk_bf16_f32 v171, v114, v115
	v_cvt_pk_bf16_f32 v172, v116, v117
	v_cvt_pk_bf16_f32 v173, v118, v119
	s_nop 1
	v_permlane16_swap_b32_e32 v170, v172
	v_permlane16_swap_b32_e32 v171, v173
	global_store_dwordx4 v[182:183], v[170:173], off offset:256
	v_or_b32_e32 v163, 16, v138
	v_mad_i64_i32 v[184:185], s[2:3], v163, s73, v[136:137]
	v_lshl_add_u64 v[184:185], v[184:185], 0, v[164:165]
	v_cvt_pk_bf16_f32 v174, v104, v105
	v_cvt_pk_bf16_f32 v175, v106, v107
	v_cvt_pk_bf16_f32 v176, v108, v109
	v_cvt_pk_bf16_f32 v177, v110, v111
	s_nop 1
	v_permlane16_swap_b32_e32 v174, v176
	v_permlane16_swap_b32_e32 v175, v177
	global_store_dwordx4 v[184:185], v[174:177], off
	v_cvt_pk_bf16_f32 v178, v96, v97
	v_cvt_pk_bf16_f32 v179, v98, v99
	v_cvt_pk_bf16_f32 v180, v100, v101
	v_cvt_pk_bf16_f32 v181, v102, v103
	s_nop 1
	v_permlane16_swap_b32_e32 v178, v180
	v_permlane16_swap_b32_e32 v179, v181
	global_store_dwordx4 v[184:185], v[178:181], off offset:256
	v_or_b32_e32 v163, 32, v138
	v_mad_i64_i32 v[186:187], s[2:3], v163, s73, v[136:137]
	v_lshl_add_u64 v[186:187], v[186:187], 0, v[164:165]
	v_cvt_pk_bf16_f32 v166, v88, v89
	v_cvt_pk_bf16_f32 v167, v90, v91
	v_cvt_pk_bf16_f32 v168, v92, v93
	v_cvt_pk_bf16_f32 v169, v94, v95
	s_nop 1
	v_permlane16_swap_b32_e32 v166, v168
	v_permlane16_swap_b32_e32 v167, v169
	global_store_dwordx4 v[186:187], v[166:169], off
	v_cvt_pk_bf16_f32 v170, v80, v81
	v_cvt_pk_bf16_f32 v171, v82, v83
	v_cvt_pk_bf16_f32 v172, v84, v85
	v_cvt_pk_bf16_f32 v173, v86, v87
	s_nop 1
	v_permlane16_swap_b32_e32 v170, v172
	v_permlane16_swap_b32_e32 v171, v173
	global_store_dwordx4 v[186:187], v[170:173], off offset:256
	v_or_b32_e32 v163, 48, v138
	v_mad_i64_i32 v[188:189], s[2:3], v163, s73, v[136:137]
	v_lshl_add_u64 v[188:189], v[188:189], 0, v[164:165]
	v_cvt_pk_bf16_f32 v174, v72, v73
	v_cvt_pk_bf16_f32 v175, v74, v75
	v_cvt_pk_bf16_f32 v176, v76, v77
	v_cvt_pk_bf16_f32 v177, v78, v79
	s_nop 1
	v_permlane16_swap_b32_e32 v174, v176
	v_permlane16_swap_b32_e32 v175, v177
	global_store_dwordx4 v[188:189], v[174:177], off
	v_cvt_pk_bf16_f32 v178, v64, v65
	v_cvt_pk_bf16_f32 v179, v66, v67
	v_cvt_pk_bf16_f32 v180, v68, v69
	v_cvt_pk_bf16_f32 v181, v70, v71
	s_nop 1
	v_permlane16_swap_b32_e32 v178, v180
	v_permlane16_swap_b32_e32 v179, v181
	global_store_dwordx4 v[188:189], v[178:181], off offset:256
	v_add_u32_e32 v163, 0x80, v138
	v_mad_i64_i32 v[182:183], s[2:3], v163, s73, v[136:137]
	v_lshl_add_u64 v[182:183], v[182:183], 0, v[164:165]
	v_cvt_pk_bf16_f32 v166, v56, v57
	v_cvt_pk_bf16_f32 v167, v58, v59
	v_cvt_pk_bf16_f32 v168, v60, v61
	v_cvt_pk_bf16_f32 v169, v62, v63
	s_nop 1
	v_permlane16_swap_b32_e32 v166, v168
	v_permlane16_swap_b32_e32 v167, v169
	global_store_dwordx4 v[182:183], v[166:169], off
	v_cvt_pk_bf16_f32 v170, v48, v49
	v_cvt_pk_bf16_f32 v171, v50, v51
	v_cvt_pk_bf16_f32 v172, v52, v53
	v_cvt_pk_bf16_f32 v173, v54, v55
	s_nop 1
	v_permlane16_swap_b32_e32 v170, v172
	v_permlane16_swap_b32_e32 v171, v173
	global_store_dwordx4 v[182:183], v[170:173], off offset:256
	v_add_u32_e32 v163, 0x90, v138
	v_mad_i64_i32 v[184:185], s[2:3], v163, s73, v[136:137]
	v_lshl_add_u64 v[184:185], v[184:185], 0, v[164:165]
	v_cvt_pk_bf16_f32 v174, v40, v41
	v_cvt_pk_bf16_f32 v175, v42, v43
	v_cvt_pk_bf16_f32 v176, v44, v45
	v_cvt_pk_bf16_f32 v177, v46, v47
	s_nop 1
	v_permlane16_swap_b32_e32 v174, v176
	v_permlane16_swap_b32_e32 v175, v177
	global_store_dwordx4 v[184:185], v[174:177], off
	v_cvt_pk_bf16_f32 v178, v32, v33
	v_cvt_pk_bf16_f32 v179, v34, v35
	v_cvt_pk_bf16_f32 v180, v36, v37
	v_cvt_pk_bf16_f32 v181, v38, v39
	s_nop 1
	v_permlane16_swap_b32_e32 v178, v180
	v_permlane16_swap_b32_e32 v179, v181
	global_store_dwordx4 v[184:185], v[178:181], off offset:256
	v_add_u32_e32 v163, 0xa0, v138
	v_mad_i64_i32 v[186:187], s[2:3], v163, s73, v[136:137]
	v_lshl_add_u64 v[186:187], v[186:187], 0, v[164:165]
	v_cvt_pk_bf16_f32 v166, v24, v25
	v_cvt_pk_bf16_f32 v167, v26, v27
	v_cvt_pk_bf16_f32 v168, v28, v29
	v_cvt_pk_bf16_f32 v169, v30, v31
	s_nop 1
	v_permlane16_swap_b32_e32 v166, v168
	v_permlane16_swap_b32_e32 v167, v169
	global_store_dwordx4 v[186:187], v[166:169], off
	v_cvt_pk_bf16_f32 v170, v16, v17
	v_cvt_pk_bf16_f32 v171, v18, v19
	v_cvt_pk_bf16_f32 v172, v20, v21
	v_cvt_pk_bf16_f32 v173, v22, v23
	s_nop 1
	v_permlane16_swap_b32_e32 v170, v172
	v_permlane16_swap_b32_e32 v171, v173
	global_store_dwordx4 v[186:187], v[170:173], off offset:256
	v_add_u32_e32 v163, 0xb0, v138
	v_mad_i64_i32 v[188:189], s[2:3], v163, s73, v[136:137]
	v_lshl_add_u64 v[188:189], v[188:189], 0, v[164:165]
	v_cvt_pk_bf16_f32 v174, v8, v9
	v_cvt_pk_bf16_f32 v175, v10, v11
	v_cvt_pk_bf16_f32 v176, v12, v13
	v_cvt_pk_bf16_f32 v177, v14, v15
	s_nop 1
	v_permlane16_swap_b32_e32 v174, v176
	v_permlane16_swap_b32_e32 v175, v177
	global_store_dwordx4 v[188:189], v[174:177], off
	v_cvt_pk_bf16_f32 v178, v0, v1
	v_cvt_pk_bf16_f32 v179, v2, v3
	v_cvt_pk_bf16_f32 v180, v4, v5
	v_cvt_pk_bf16_f32 v181, v6, v7
	s_nop 1
	v_permlane16_swap_b32_e32 v178, v180
	v_permlane16_swap_b32_e32 v179, v181
	global_store_dwordx4 v[188:189], v[178:181], off offset:256
	s_branch .LBB0_324

.LBB0_522:
	s_andn2_b64 vcc, exec, s[36:37]
	s_cbranch_vccnz .LBB0_548
	s_lshr_b32 s2, s18, 31
	s_add_i32 s2, s18, s2
	s_ashr_i32 s2, s2, 1
	s_cmp_lt_i32 s20, s2
	s_cbranch_scc1 .Ltr_low
	s_sub_i32 s3, s20, s2
	s_mov_b32 s9, 0
	s_movk_i32 s83, 0x18ff
	s_branch .Ltr_go
.Ltr_low:
	s_mov_b32 s3, s20
	s_movk_i32 s9, 0x1900
.Ltr_go:
	s_waitcnt vmcnt(0)
	v_ashrrev_i32_e32 v0, 6, v160
	s_waitcnt lgkmcnt(0)
	v_lshl_add_u32 v1, s3, 3, v0
	v_add_u32_e32 v1, s9, v1
	s_add_i32 s3, s83, 1
	v_cmp_gt_i32_e32 vcc, s3, v1
	s_barrier
	s_and_saveexec_b64 s[36:37], vcc
	s_cbranch_execz .LBB0_547
	s_movk_i32 s3, 0x2100
	v_mul_lo_u32 v0, v0, s3
	v_add_u32_e32 v4, 0, v0
	v_bfe_u32 v15, v160, 5, 1
	v_and_b32_e32 v0, 31, v160
	v_lshlrev_b32_e32 v2, 2, v0
	v_mul_u32_u24_e32 v3, 0x84, v15
	v_add3_u32 v18, v4, v2, v3
	v_lshlrev_b32_e32 v2, 3, v160
	v_and_b32_e32 v2, 56, v2
	v_lshlrev_b32_e32 v156, 1, v2
	v_bfe_u32 v19, v160, 3, 3
	v_lshl_add_u64 v[12:13], s[26:27], 0, v[156:157]
	s_mov_b64 s[6:7], 0x18204000
	v_mul_u32_u24_e32 v5, 0x84, v2
	v_lshl_add_u64 v[2:3], v[12:13], 0, s[6:7]
	v_lshlrev_b32_e32 v20, 2, v19
	s_mov_b64 s[6:7], 0x17dc4000
	v_add3_u32 v21, v4, v5, v20
	v_lshl_add_u64 v[4:5], v[12:13], 0, s[6:7]
	s_mov_b64 s[6:7], 0x18f04000
	v_lshl_add_u64 v[6:7], v[12:13], 0, s[6:7]
	s_mov_b64 s[6:7], 0x17844000
	v_lshl_add_u64 v[8:9], v[12:13], 0, s[6:7]
	s_mov_b64 s[6:7], 0x18404000
	s_sub_i32 s10, s18, s2
	v_lshl_add_u64 v[10:11], v[12:13], 0, s[6:7]
	s_mov_b64 s[6:7], 0x16d44000
	s_lshl_b32 s2, s10, 3
	v_or_b32_e32 v22, 8, v19
	v_or_b32_e32 v23, 16, v19
	v_or_b32_e32 v24, 24, v19
	v_and_b32_e32 v25, 16, v20
	v_lshl_add_u64 v[12:13], v[12:13], 0, s[6:7]
	v_lshlrev_b32_e32 v26, 5, v1
	s_lshl_b32 s3, s10, 8
	v_lshl_or_b32 v14, v1, 7, v20
	s_lshl_b32 s9, s10, 10
	v_lshl_add_u32 v27, v1, 1, v203
	s_lshl_b32 s19, s10, 4
	s_mov_b64 s[38:39], 0
	s_branch .LBB0_527

.LBB0_547:
	s_or_b64 exec, exec, s[36:37]
	s_movk_i32 s83, 0x24af
